# scan producer: row index of steps 1..7 of a wave derived from step 0 (one add) instead of re-deriving it through four branches
# speedup vs baseline: 1.0652x; 1.0067x over previous
.LBB0_1686:
	s_mov_b32 s58, s2
	s_ashr_i32 s3, s2, 31
	s_lshl_b64 s[16:17], s[2:3], 11
	v_lshl_add_u64 v[14:15], v[0:1], 0, s[16:17]
	global_load_ushort v49, v[14:15], off
	v_lshl_add_u64 v[14:15], v[2:3], 0, s[16:17]
	global_load_ushort v55, v[14:15], off
	v_lshl_add_u64 v[14:15], v[6:7], 0, s[16:17]
	s_lshl_b64 s[2:3], s[2:3], 6
	global_load_ushort v52, v[14:15], off
	v_lshl_add_u64 v[14:15], v[8:9], 0, s[16:17]
	s_add_u32 s2, s65, s2
	global_load_ushort v67, v[14:15], off
	v_lshl_add_u64 v[14:15], v[4:5], 0, s[16:17]
	s_addc_u32 s3, s66, s3
	global_load_ushort v51, v[14:15], off
	global_load_dword v53, v153, s[2:3]
	s_cmp_lg_u64 s[0:1], 0
	s_cselect_b32 s3, -1, 1
	s_add_i32 s2, s58, s3
	s_ashr_i32 s3, s2, 31
	s_lshl_b64 s[16:17], s[2:3], 11
	v_lshl_add_u64 v[14:15], v[0:1], 0, s[16:17]
	global_load_ushort v70, v[14:15], off
	v_lshl_add_u64 v[14:15], v[2:3], 0, s[16:17]
	global_load_ushort v74, v[14:15], off
	v_lshl_add_u64 v[14:15], v[6:7], 0, s[16:17]
	s_lshl_b64 s[2:3], s[2:3], 6
	global_load_ushort v72, v[14:15], off
	v_lshl_add_u64 v[14:15], v[8:9], 0, s[16:17]
	s_add_u32 s2, s65, s2
	global_load_ushort v78, v[14:15], off
	v_lshl_add_u64 v[14:15], v[4:5], 0, s[16:17]
	s_addc_u32 s3, s66, s3
	global_load_ushort v71, v[14:15], off
	global_load_dword v73, v153, s[2:3]
	s_cmp_lg_u64 s[0:1], 0
	s_cselect_b32 s3, -2, 2
	s_add_i32 s2, s58, s3
	s_ashr_i32 s3, s2, 31
	s_lshl_b64 s[16:17], s[2:3], 11
	v_lshl_add_u64 v[14:15], v[0:1], 0, s[16:17]
	global_load_ushort v54, v[14:15], off
	v_lshl_add_u64 v[14:15], v[2:3], 0, s[16:17]
	global_load_ushort v68, v[14:15], off
	v_lshl_add_u64 v[14:15], v[6:7], 0, s[16:17]
	s_lshl_b64 s[2:3], s[2:3], 6
	global_load_ushort v59, v[14:15], off
	v_lshl_add_u64 v[14:15], v[8:9], 0, s[16:17]
	s_add_u32 s2, s65, s2
	global_load_ushort v69, v[14:15], off
	v_lshl_add_u64 v[14:15], v[4:5], 0, s[16:17]
	s_addc_u32 s3, s66, s3
	global_load_ushort v56, v[14:15], off
	global_load_dword v58, v153, s[2:3]
	s_cmp_lg_u64 s[0:1], 0
	s_cselect_b32 s3, -3, 3
	s_add_i32 s2, s58, s3
	s_ashr_i32 s3, s2, 31
	s_lshl_b64 s[16:17], s[2:3], 11
	v_lshl_add_u64 v[14:15], v[0:1], 0, s[16:17]
	global_load_ushort v43, v[14:15], off
	v_lshl_add_u64 v[14:15], v[2:3], 0, s[16:17]
	global_load_ushort v48, v[14:15], off
	v_lshl_add_u64 v[14:15], v[6:7], 0, s[16:17]
	s_lshl_b64 s[2:3], s[2:3], 6
	global_load_ushort v46, v[14:15], off
	v_lshl_add_u64 v[14:15], v[8:9], 0, s[16:17]
	s_add_u32 s2, s65, s2
	global_load_ushort v50, v[14:15], off
	v_lshl_add_u64 v[14:15], v[4:5], 0, s[16:17]
	s_addc_u32 s3, s66, s3
	global_load_ushort v44, v[14:15], off
	global_load_dword v45, v153, s[2:3]
	s_cmp_lg_u64 s[0:1], 0
	s_cselect_b32 s3, -4, 4
	s_add_i32 s2, s58, s3
	s_ashr_i32 s3, s2, 31
	s_lshl_b64 s[16:17], s[2:3], 11
	v_lshl_add_u64 v[14:15], v[0:1], 0, s[16:17]
	global_load_ushort v36, v[14:15], off
	v_lshl_add_u64 v[14:15], v[2:3], 0, s[16:17]
	global_load_ushort v41, v[14:15], off
	v_lshl_add_u64 v[14:15], v[6:7], 0, s[16:17]
	s_lshl_b64 s[2:3], s[2:3], 6
	global_load_ushort v40, v[14:15], off
	v_lshl_add_u64 v[14:15], v[8:9], 0, s[16:17]
	s_add_u32 s2, s65, s2
	global_load_ushort v42, v[14:15], off
	v_lshl_add_u64 v[14:15], v[4:5], 0, s[16:17]
	s_addc_u32 s3, s66, s3
	global_load_ushort v39, v[14:15], off
	global_load_dword v38, v153, s[2:3]
	s_cmp_lg_u64 s[0:1], 0
	s_cselect_b32 s3, -5, 5
	s_add_i32 s2, s58, s3
	s_ashr_i32 s3, s2, 31
	s_lshl_b64 s[16:17], s[2:3], 11
	v_lshl_add_u64 v[14:15], v[0:1], 0, s[16:17]
	global_load_ushort v26, v[14:15], off
	v_lshl_add_u64 v[14:15], v[2:3], 0, s[16:17]
	global_load_ushort v31, v[14:15], off
	v_lshl_add_u64 v[14:15], v[6:7], 0, s[16:17]
	s_lshl_b64 s[2:3], s[2:3], 6
	global_load_ushort v29, v[14:15], off
	v_lshl_add_u64 v[14:15], v[8:9], 0, s[16:17]
	s_add_u32 s2, s65, s2
	global_load_ushort v33, v[14:15], off
	v_lshl_add_u64 v[14:15], v[4:5], 0, s[16:17]
	s_addc_u32 s3, s66, s3
	global_load_ushort v28, v[14:15], off
	global_load_dword v27, v153, s[2:3]
	s_cmp_lg_u64 s[0:1], 0
	s_cselect_b32 s3, -6, 6
	s_add_i32 s2, s58, s3
	s_ashr_i32 s3, s2, 31
	s_lshl_b64 s[16:17], s[2:3], 11
	v_lshl_add_u64 v[14:15], v[0:1], 0, s[16:17]
	global_load_ushort v19, v[14:15], off
	v_lshl_add_u64 v[14:15], v[2:3], 0, s[16:17]
	global_load_ushort v23, v[14:15], off
	v_lshl_add_u64 v[14:15], v[6:7], 0, s[16:17]
	s_lshl_b64 s[2:3], s[2:3], 6
	global_load_ushort v22, v[14:15], off
	v_lshl_add_u64 v[14:15], v[8:9], 0, s[16:17]
	s_add_u32 s2, s65, s2
	global_load_ushort v24, v[14:15], off
	v_lshl_add_u64 v[14:15], v[4:5], 0, s[16:17]
	s_addc_u32 s3, s66, s3
	global_load_ushort v21, v[14:15], off
	global_load_dword v20, v153, s[2:3]
	s_cmp_lg_u64 s[0:1], 0
	s_cselect_b32 s3, -7, 7
	s_add_i32 s2, s58, s3
	s_ashr_i32 s3, s2, 31
	s_lshl_b64 s[16:17], s[2:3], 11
	v_lshl_add_u64 v[14:15], v[0:1], 0, s[16:17]
	global_load_ushort v13, v[14:15], off
	v_lshl_add_u64 v[14:15], v[2:3], 0, s[16:17]
	global_load_ushort v17, v[14:15], off
	v_lshl_add_u64 v[14:15], v[6:7], 0, s[16:17]
	s_lshl_b64 s[2:3], s[2:3], 6
	global_load_ushort v16, v[14:15], off
	v_lshl_add_u64 v[14:15], v[8:9], 0, s[16:17]
	s_add_u32 s2, s65, s2
	global_load_ushort v18, v[14:15], off
	v_lshl_add_u64 v[14:15], v[4:5], 0, s[16:17]
	s_addc_u32 s3, s66, s3
	global_load_ushort v15, v[14:15], off
	v_cvt_f32_f16_e32 v100, v96
	global_load_dword v14, v153, s[2:3]
	v_cvt_f32_f16_e32 v102, v99
	s_add_i32 s80, s61, 32
	s_and_b32 s2, s80, 32
	v_mul_f32_e32 v85, v10, v85
	s_add_i32 s2, s2, s75
	v_mul_f32_e32 v103, v85, v100
	v_add_f32_e32 v85, -1.0, v102
	s_mulk_i32 s2, 0x540
	v_fma_f32 v85, v12, v85, 1.0
	v_mul_f32_e32 v100, v85, v100
	v_add_u32_e32 v85, s2, v84
	v_mul_f32_e64 v102, v103, -v102
	v_mov_b32_e32 v104, 1.0
	v_mul_f32_e32 v105, v103, v104
	v_mov_b32_e32 v106, v102
	v_cvt_f32_f16_e32 v102, v97
	v_cvt_f32_f16_e32 v101, v95
	v_sub_f32_e32 v102, 1.0, v102
	v_mul_f32_e32 v104, v104, v102
	v_rcp_f32_e32 v107, v104
	s_nop 0
	v_mul_f32_e32 v106, v106, v107
	v_mul_f32_e32 v108, v100, v107
	ds_write2st64_b32 v85, v105, v106 offset1:1
	ds_write2st64_b32 v85, v108, v104 offset0:2 offset1:3
	v_mul_f32_e32 v107, v101, v104
	ds_write_b32 v85, v107 offset:1024
	s_and_saveexec_b64 s[2:3], s[10:11]
	v_cvt_f32_f16_e32 v102, v98
	ds_write_b32 v85, v102 offset:1280
	s_or_b64 exec, exec, s[2:3]
	s_add_i32 s60, s60, 1
	s_lshl_b32 s82, s60, 5
	s_and_b64 vcc, exec, s[14:15]
	s_add_i32 s82, s82, s75
	s_and_b32 s2, s55, 3
	s_cmp_lg_u32 s2, 0
	s_cbranch_scc1 .LBB0_1780
	v_mul_f32_e32 v100, v100, v101
	v_mul_f32_e32 v101, v11, v100
	s_nop 1
	v_mov_b32_dpp v101, v101 quad_perm:[1,0,3,2] row_mask:0xf bank_mask:0xf bound_ctrl:1
	v_fmac_f32_e32 v101, v11, v100
	s_nop 1
	v_add_f32_dpp v100, v101, v101 quad_perm:[2,3,0,1] row_mask:0xf bank_mask:0xf bound_ctrl:1
	s_nop 1
	v_add_f32_dpp v100, v100, v100 row_half_mirror row_mask:0xf bank_mask:0xf bound_ctrl:1
	s_nop 1
	v_add_f32_dpp v100, v100, v100 row_mirror row_mask:0xf bank_mask:0xf bound_ctrl:1
	v_mov_b32_e32 v101, v100
	s_nop 1
	v_permlane16_swap_b32 v100, v101
	s_nop 1
	s_nop 0
	v_add_f32_e32 v100, v100, v101
	v_mov_b32_e32 v101, v100
	s_nop 1
	v_permlane32_swap_b32 v100, v101
	s_nop 1
	s_and_saveexec_b64 s[2:3], s[12:13]
	s_cbranch_execz .LBB0_1779
	s_cmpk_gt_i32 s67, 0xff
	s_mov_b64 s[58:59], -1
	s_cbranch_scc0 .LBB0_1773
	s_andn2_b64 vcc, exec, s[0:1]
	s_cbranch_vccnz .LBB0_1770
	s_sub_i32 s16, s44, s82
	s_mov_b64 s[58:59], 0
